# NA bias reads: one per-lane LDS base per query row + immediate offsets instead of 16 per-read address computations per step
# speedup vs baseline: 1.0023x; 1.0001x over previous
; __device__ __forceinline__ void na_item(unsigned char* smem, const bf16_t* U, const float* rpb_l, bf16_t* O, int b, int rp, int hp, float shift) {
;     ...
;     const int rsA = min(max(rA - 4, 0), 24), rsB = min(max(rB - 4, 0), 24), dB = rsB - rsA, nst = dB + 8;
;     const int kcol0 = min(max(16 * qg - 8, 0), 32);
;     const int qc = 16 * qg + fr, cs = min(max(qc - 8, 0), 48);
;     const size_t qrowA = (size_t)b * SEQ + rA * 64 + qc, qrowB = qrowA + 64;
;     bf16x8_t qfA[2], qfB[2];
; #pragma unroll
;     for (int kk = 0; kk < 2; ++kk) { qfA[kk] = *(const bf16x8_t*)(U + qrowA * NINP + OQ + h * 64 + kk * 32 + fq * 8); qfB[kk] = *(const bf16x8_t*)(U + qrowB * NINP + OQ + h * 64 + kk * 32 + fq * 8); }
;     f32x4_t oA[4], oB[4];
; #pragma unroll
;     for (int dg = 0; dg < 4; ++dg) { oA[dg] = (f32x4_t){0.f, 0.f, 0.f, 0.f}; oB[dg] = (f32x4_t){0.f, 0.f, 0.f, 0.f}; }
;     float lA = 0.f, lB = 0.f;
;     const float nsh = -shift;
;     const int srow = tid >> 3, sch = tid & 7;
;     const int crow = (tid & 255) >> 3, cisv = tid >> 8;
;     const size_t latbase = ((size_t)b * SEQ + (size_t)rsA * 64 + srow) * NINP + sch * 8;
;     const size_t ctxbase = ((size_t)NLAT + b * CTXL + crow) * NINP + (cisv ? OV : OKK) + sch * 8;
;     ...
;                 const int kc = kcol0 + 16 * g + 4 * fq + j;
;                 const bool valid = (kc >= cs) && (kc < cs + 16);
;                 const int idx = min(max(kc - qc + 15, 0), 30);
.LBB0_846:
	s_andn2_b64 vcc, exec, s[2:3]
	s_mov_b32 s78, 0
	s_cbranch_vccnz .LBB0_893
	v_add_u32_e32 v2, v65, v61
	v_add_u32_e32 v3, v65, v120
	v_mul_u32_u24_e32 v126, 0x90, v2
	v_sub_u32_e32 v2, v3, v60
	v_sub_u32_e32 v228, v3, v60
	v_add_u32_e32 v228, 15, v228
	v_lshlrev_b32_e32 v228, 2, v228
	v_max_i32_e32 v2, -15, v2
	v_add_u32_e32 v4, 16, v57
	v_add_u32_e32 v2, 15, v2
	v_cmp_ge_u32_e32 vcc, v3, v57
	v_cmp_lt_u32_e64 s[38:39], v3, v4
	v_min_u32_e32 v128, 30, v2
	v_or_b32_e32 v2, 1, v3
	s_and_b64 s[20:21], vcc, s[38:39]
	v_cmp_ge_u32_e32 vcc, v2, v57
	v_cmp_lt_u32_e64 s[38:39], v2, v4
	v_sub_u32_e32 v2, v2, v60
	v_max_i32_e32 v2, -15, v2
	v_add_u32_e32 v2, 15, v2
	v_min_u32_e32 v129, 30, v2
	v_or_b32_e32 v2, 2, v3
	s_and_b64 s[40:41], vcc, s[38:39]
	v_cmp_ge_u32_e32 vcc, v2, v57
	v_cmp_lt_u32_e64 s[38:39], v2, v4
	v_sub_u32_e32 v2, v2, v60
	v_max_i32_e32 v2, -15, v2
	v_add_u32_e32 v2, 15, v2
	v_min_u32_e32 v130, 30, v2
	v_or_b32_e32 v2, 3, v3
	s_and_b64 s[16:17], vcc, s[38:39]
	v_cmp_ge_u32_e32 vcc, v2, v57
	v_cmp_lt_u32_e64 s[38:39], v2, v4
	v_sub_u32_e32 v2, v2, v60
	v_max_i32_e32 v2, -15, v2
	v_add_u32_e32 v2, 15, v2
	s_movk_i32 s2, 0x6c00
	v_min_u32_e32 v131, 30, v2
	v_add_u32_e32 v2, 16, v3
	v_mad_i32_i24 v121, v63, s2, 0
	s_and_b64 s[2:3], vcc, s[38:39]
	v_cmp_ge_u32_e32 vcc, v2, v57
	v_sub_u32_e32 v2, v2, v60
	v_max_i32_e32 v2, -15, v2
	v_add_u32_e32 v2, 15, v2
	v_cmp_lt_u32_e64 s[38:39], v3, v57
	v_min_u32_e32 v132, 30, v2
	v_add_u32_e32 v2, 17, v3
	s_sub_i32 s97, s27, s26
	s_and_b64 s[26:27], vcc, s[38:39]
	v_cmp_ge_u32_e32 vcc, v2, v57
	v_cmp_lt_u32_e64 s[38:39], v2, v4
	v_sub_u32_e32 v2, v2, v60
	v_max_i32_e32 v2, -15, v2
	v_add_u32_e32 v2, 15, v2
	v_min_u32_e32 v133, 30, v2
	v_add_u32_e32 v2, 18, v3
	s_and_b64 s[74:75], vcc, s[38:39]
	v_cmp_ge_u32_e32 vcc, v2, v57
	v_cmp_lt_u32_e64 s[38:39], v2, v4
	v_sub_u32_e32 v2, v2, v60
	v_max_i32_e32 v2, -15, v2
	v_add_u32_e32 v2, 15, v2
	v_min_u32_e32 v134, 30, v2
	v_add_u32_e32 v2, 19, v3
	s_and_b64 s[52:53], vcc, s[38:39]
	v_cmp_ge_u32_e32 vcc, v2, v57
	v_cmp_lt_u32_e64 s[38:39], v2, v4
	v_sub_u32_e32 v2, v2, v60
	v_lshlrev_b32_e32 v5, 3, v62
	v_max_i32_e32 v2, -15, v2
	s_add_i32 s13, s5, 8
	v_and_b32_e32 v123, 24, v5
	v_lshrrev_b32_e32 v5, 2, v61
	s_and_b64 s[38:39], vcc, s[38:39]
	v_add_u32_e32 v2, 15, v2
	v_mov_b32_e32 v111, v0
	v_mov_b32_e32 v57, v0
	v_or_b32_e32 v6, v120, v5
	v_or_b32_e32 v5, v3, v5
	v_min_u32_e32 v135, 30, v2
	v_lshl_add_u64 v[2:3], v[110:111], 0, v[56:57]
	s_add_u32 s28, s83, s54
	v_lshl_add_u64 v[2:3], v[54:55], 1, v[2:3]
	s_addc_u32 s29, s84, 0
	v_lshl_add_u64 v[114:115], s[28:29], 0, v[2:3]
	s_add_u32 s28, s85, s54
	v_lshl_add_u64 v[2:3], v[58:59], 0, v[110:111]
	s_addc_u32 s29, s86, 0
	v_mov_b32_e32 v58, 0
	v_mul_i32_i24_e32 v122, 15, v63
	v_mul_u32_u24_e32 v124, 0x90, v6
	v_mul_u32_u24_e32 v125, 0x90, v5
	v_mul_u32_u24_e32 v127, 0x90, v61
	v_lshl_add_u64 v[116:117], s[28:29], 0, v[2:3]
	v_mov_b32_e32 v59, v58
	v_mov_b32_e32 v60, v58
	v_mov_b32_e32 v61, v58
	v_mov_b32_e32 v62, v58
	v_mov_b32_e32 v63, v58
	v_mov_b32_e32 v64, v58
	v_mov_b32_e32 v65, v58
	v_mov_b32_e32 v66, v58
	v_mov_b32_e32 v67, v58
	v_mov_b32_e32 v68, v58
	v_mov_b32_e32 v69, v58
	v_mov_b32_e32 v70, v58
	v_mov_b32_e32 v71, v58
	v_mov_b32_e32 v72, v58
	v_mov_b32_e32 v73, v58
	v_mov_b32_e32 v10, v58
	v_mov_b32_e32 v11, v58
	v_mov_b32_e32 v12, v58
	v_mov_b32_e32 v13, v58
	v_mov_b32_e32 v6, v58
	v_mov_b32_e32 v7, v58
	v_mov_b32_e32 v8, v58
	v_mov_b32_e32 v9, v58
	v_mov_b32_e32 v2, v58
	v_mov_b32_e32 v3, v58
	v_mov_b32_e32 v4, v58
	v_mov_b32_e32 v5, v58
	v_mov_b32_e32 v54, v58
	v_mov_b32_e32 v55, v58
	v_mov_b32_e32 v56, v58
	v_mov_b32_e32 v57, v58
	v_mov_b32_e32 v112, v58
	v_mov_b32_e32 v113, v58

; #define LASP __attribute__((address_space(3)))
; __device__ __forceinline__ void na_item(unsigned char* smem, const bf16_t* U, const float* rpb_l, bf16_t* O, int b, int rp, int hp, float shift) {
;     ...
;     for (int i = 0; i < nst; ++i) {
;         if (i + 1 < nst) NA_STORE(i + 1);
;         if (i + 2 < nst) NA_LOAD(i + 2);
;         LASP unsigned char* base = ls + (i & 1) * BUF + hh * HSZ;
;         const bool hasctx = i < 8, latA = i < 8, latB = (i >= dB);
;         f32x4_t sA[4], sB[4];
; #pragma unroll
;         for (int g = 0; g < 4; ++g) { sA[g] = (f32x4_t){nsh, nsh, nsh, nsh}; sB[g] = (f32x4_t){nsh, nsh, nsh, nsh}; }
; #pragma unroll
;         for (int kk = 0; kk < 2; ++kk) {
; #pragma unroll
;             for (int g = 0; g < 2; ++g) {
;                 const bf16x8_t kl = *(const LASP bf16x8_t*)(base + (kcol0 + 16 * g + fr) * KR + (kk * 32 + fq * 8) * 2);
;                 sA[g] = __builtin_amdgcn_mfma_f32_16x16x32_bf16(kl, qfA[kk], sA[g], 0, 0, 0);
;                 sB[g] = __builtin_amdgcn_mfma_f32_16x16x32_bf16(kl, qfB[kk], sB[g], 0, 0, 0);
;                 const bf16x8_t kc = *(const LASP bf16x8_t*)(base + O_KC + (16 * g + fr) * KR + (kk * 32 + fq * 8) * 2);
;                 sA[2 + g] = __builtin_amdgcn_mfma_f32_16x16x32_bf16(kc, qfA[kk], sA[2 + g], 0, 0, 0);
;                 sB[2 + g] = __builtin_amdgcn_mfma_f32_16x16x32_bf16(kc, qfB[kk], sB[2 + g], 0, 0, 0);
;             }
;         }
;         const int relA = rsA + i - rA + 7, relB = relA - 1;
;         const int brA = min(max(relA, 0), 14), brB = min(max(relB, 0), 14);
; #pragma unroll
;         for (int g = 0; g < 2; ++g)
; #pragma unroll
;             for (int j = 0; j < 4; ++j) {
;                 const int kc = kcol0 + 16 * g + 4 * fq + j;
;                 const bool valid = (kc >= cs) && (kc < cs + 16);
;                 const int idx = min(max(kc - qc + 15, 0), 30);
;                 sA[g][j] = (valid && latA) ? sA[g][j] + bias[(hh * 15 + brA) * 32 + idx] : -INFINITY;
;                 sB[g][j] = (valid && latB) ? sB[g][j] + bias[(hh * 15 + brB) * 32 + idx] : -INFINITY;
;             }
.LBB0_859:
	s_bitcmp1_b32 s78, 0
	s_cselect_b32 s18, 0xd800, 0
	v_add_u32_e32 v111, s18, v121
	v_add_u32_e32 v86, v111, v108
	v_add_u32_e32 v144, v86, v126
	ds_read_b128 v[164:167], v144 offset:2304
	ds_read_b128 v[168:171], v144
	v_mov_b64_e32 v[80:81], s[62:63]
	v_mov_b64_e32 v[78:79], s[60:61]
	v_add_u32_e32 v145, v86, v127
	ds_read_b128 v[172:175], v145 offset:18432
	ds_read_b128 v[176:179], v145 offset:20736
	ds_read_b128 v[200:203], v144 offset:64
	ds_read_b128 v[204:207], v145 offset:18496
	s_cmp_lt_u32 s78, 8
	s_cselect_b64 vcc, -1, 0
	s_add_i32 s79, s97, s78
	ds_read_b128 v[212:215], v144 offset:2368
	s_waitcnt lgkmcnt(6)
	v_mfma_f32_16x16x32_bf16 v[136:139], v[164:167], v[14:17], v[78:81]
	s_max_i32 s18, s79, -7
	s_add_i32 s18, s18, 7
	s_min_u32 s18, s18, 14
	v_mfma_f32_16x16x32_bf16 v[140:143], v[164:167], v[22:25], v[78:81]
	ds_read_b128 v[164:167], v145 offset:20800
	s_waitcnt lgkmcnt(6)
	v_mfma_f32_16x16x32_bf16 v[82:85], v[168:171], v[14:17], v[78:81]
	v_mfma_f32_16x16x32_bf16 v[74:77], v[168:171], v[22:25], v[78:81]
	s_waitcnt lgkmcnt(5)
	v_mfma_f32_16x16x32_bf16 v[90:93], v[172:175], v[14:17], v[78:81]
	v_mfma_f32_16x16x32_bf16 v[86:89], v[172:175], v[22:25], v[78:81]
	s_waitcnt lgkmcnt(4)
	v_mfma_f32_16x16x32_bf16 v[156:159], v[176:179], v[14:17], v[78:81]
	v_mfma_f32_16x16x32_bf16 v[160:163], v[176:179], v[22:25], v[78:81]
	s_nop 2
	s_waitcnt lgkmcnt(3)
	v_mfma_f32_16x16x32_bf16 v[102:105], v[200:203], v[18:21], v[82:85]
	s_nop 2
	v_mfma_f32_16x16x32_bf16 v[98:101], v[200:203], v[26:29], v[74:77]
	s_waitcnt lgkmcnt(2)
	v_mfma_f32_16x16x32_bf16 v[74:77], v[204:207], v[18:21], v[90:93]
	v_mfma_f32_16x16x32_bf16 v[78:81], v[204:207], v[26:29], v[86:89]
	s_nop 2
	s_waitcnt lgkmcnt(1)
	v_mfma_f32_16x16x32_bf16 v[94:97], v[212:215], v[18:21], v[136:139]
	v_mfma_f32_16x16x32_bf16 v[90:93], v[212:215], v[26:29], v[140:143]
	s_nop 1
	v_add_u32_e32 v136, s18, v122
	v_lshl_add_u32 v138, v136, 7, s4
	v_add_u32_e32 v229, v138, v228
	s_waitcnt lgkmcnt(0)
	v_mfma_f32_16x16x32_bf16 v[82:85], v[164:167], v[18:21], v[156:159]
	s_cmp_ge_i32 s78, s5
	s_cselect_b64 s[76:77], -1, 0
	s_max_i32 s18, s79, -6
	s_add_i32 s18, s18, 6
	s_min_u32 s18, s18, 14
	v_mfma_f32_16x16x32_bf16 v[86:89], v[164:167], v[26:29], v[160:163]
	v_add_u32_e32 v139, s18, v122
	v_lshl_add_u32 v139, v139, 7, s4
	v_add_u32_e32 v230, v139, v228
	ds_read_b32 v180, v229
	ds_read_b32 v181, v230
	ds_read_b32 v182, v229 offset:4
	ds_read_b32 v183, v230 offset:4
	ds_read_b32 v184, v229 offset:8
	ds_read_b32 v185, v230 offset:8
	ds_read_b32 v186, v229 offset:12
	ds_read_b32 v187, v230 offset:12
	ds_read_b32 v188, v229 offset:64
	ds_read_b32 v189, v230 offset:64
	ds_read_b32 v190, v229 offset:68
	ds_read_b32 v191, v230 offset:68
	ds_read_b32 v192, v229 offset:72
	ds_read_b32 v193, v230 offset:72
	s_waitcnt lgkmcnt(12)
	s_and_b64 s[18:19], s[20:21], vcc
	v_add_f32_e32 v180, v102, v180
	v_cndmask_b32_e64 v137, v154, v180, s[18:19]
	s_and_b64 s[18:19], s[20:21], s[76:77]
	v_add_f32_e32 v181, v98, v181
	v_cndmask_b32_e64 v136, v154, v181, s[18:19]
	ds_read_b32 v194, v229 offset:76
	ds_read_b32 v195, v230 offset:76
	s_waitcnt lgkmcnt(12)
	s_and_b64 s[18:19], s[40:41], vcc
	v_add_f32_e32 v182, v103, v182
	v_cndmask_b32_e64 v102, v154, v182, s[18:19]
	s_and_b64 s[18:19], s[40:41], s[76:77]
	v_add_f32_e32 v183, v99, v183
	v_cndmask_b32_e64 v98, v154, v183, s[18:19]
	s_waitcnt lgkmcnt(10)
	s_and_b64 s[18:19], s[16:17], vcc
	v_add_f32_e32 v184, v104, v184
	v_cndmask_b32_e64 v103, v154, v184, s[18:19]
	s_and_b64 s[18:19], s[16:17], s[76:77]
	v_add_f32_e32 v185, v100, v185
	v_cndmask_b32_e64 v99, v154, v185, s[18:19]
	s_waitcnt lgkmcnt(8)
	s_and_b64 s[18:19], s[2:3], vcc
	v_add_f32_e32 v186, v105, v186
	v_cndmask_b32_e64 v104, v154, v186, s[18:19]
	s_and_b64 s[18:19], s[2:3], s[76:77]
	v_add_f32_e32 v187, v101, v187
	v_cndmask_b32_e64 v100, v154, v187, s[18:19]
	s_waitcnt lgkmcnt(6)
	s_and_b64 s[18:19], s[26:27], vcc
	v_add_f32_e32 v188, v94, v188
	v_cndmask_b32_e64 v105, v154, v188, s[18:19]
	s_and_b64 s[18:19], s[26:27], s[76:77]
	v_add_f32_e32 v189, v90, v189
	v_cndmask_b32_e64 v101, v154, v189, s[18:19]
	s_waitcnt lgkmcnt(4)
	s_and_b64 s[18:19], s[74:75], vcc
	v_add_f32_e32 v190, v95, v190
	v_cndmask_b32_e64 v140, v154, v190, s[18:19]
	s_and_b64 s[18:19], s[74:75], s[76:77]
	v_add_f32_e32 v191, v91, v191
	v_cndmask_b32_e64 v94, v154, v191, s[18:19]
	s_waitcnt lgkmcnt(2)
	s_and_b64 s[18:19], s[52:53], vcc
	v_add_f32_e32 v192, v96, v192
	v_cndmask_b32_e64 v91, v154, v192, s[18:19]
	s_and_b64 s[18:19], s[52:53], s[76:77]
	v_add_f32_e32 v193, v92, v193
	v_cndmask_b32_e64 v90, v154, v193, s[18:19]
	s_waitcnt lgkmcnt(0)
; #define LASP __attribute__((address_space(3)))
; __device__ __forceinline__ void na_item(unsigned char* smem, const bf16_t* U, const float* rpb_l, bf16_t* O, int b, int rp, int hp, float shift) {
;     ...
;         if (!hasctx) {
; #pragma unroll
;             for (int g = 2; g < 4; ++g) { sA[g] = (f32x4_t){-INFINITY, -INFINITY, -INFINITY, -INFINITY}; sB[g] = sA[g]; }
;         }
;         { float psA = 0.f, psB = 0.f;
; #pragma unroll
;           for (int g = 0; g < 4; ++g)
; #pragma unroll
;               for (int j = 0; j < 4; ++j) { const float pa = __builtin_amdgcn_exp2f(sA[g][j]); sA[g][j] = pa; psA += pa;
;                                             const float pb_ = __builtin_amdgcn_exp2f(sB[g][j]); sB[g][j] = pb_; psB += pb_; }
;           lA += psA; lB += psB; }
; #pragma unroll
;         for (int kp = 0; kp < 2; ++kp) {
;             u32x4_t pk;
;             pk.x = pg8::cvt_pk_bf16(sA[2 * kp][0], sA[2 * kp][1]); pk.y = pg8::cvt_pk_bf16(sA[2 * kp][2], sA[2 * kp][3]); pk.z = pg8::cvt_pk_bf16(sA[2 * kp + 1][0], sA[2 * kp + 1][1]); pk.w = pg8::cvt_pk_bf16(sA[2 * kp + 1][2], sA[2 * kp + 1][3]);
;             const bf16x8_t pbA = __builtin_bit_cast(bf16x8_t, pk);
;             pk.x = pg8::cvt_pk_bf16(sB[2 * kp][0], sB[2 * kp][1]); pk.y = pg8::cvt_pk_bf16(sB[2 * kp][2], sB[2 * kp][3]); pk.z = pg8::cvt_pk_bf16(sB[2 * kp + 1][0], sB[2 * kp + 1][1]); pk.w = pg8::cvt_pk_bf16(sB[2 * kp + 1][2], sB[2 * kp + 1][3]);
;             const bf16x8_t pbB = __builtin_bit_cast(bf16x8_t, pk);
;             LASP unsigned char* vb = kp == 0 ? base + O_VL + (kcol0 + 4 * fq + (fr >> 2)) * KR : base + O_VC + (4 * fq + (fr >> 2)) * KR;
; #pragma unroll
;             for (int dg = 0; dg < 4; ++dg) {
;                 LASP unsigned char* va = vb + (16 * dg + 4 * (fr & 3)) * 2;
;                 const s16x4 v0 = __builtin_amdgcn_ds_read_tr16_b64_v4i16((LASP s16x4*)va);
;                 const s16x4 v1 = __builtin_amdgcn_ds_read_tr16_b64_v4i16((LASP s16x4*)(va + 16 * KR));
;                 const bf16x8_t vf = __builtin_shufflevector(v0, v1, 0, 1, 2, 3, 4, 5, 6, 7);
;                 oA[dg] = __builtin_amdgcn_mfma_f32_16x16x32_bf16(vf, pbA, oA[dg], 0, 0, 0);
;                 oB[dg] = __builtin_amdgcn_mfma_f32_16x16x32_bf16(vf, pbB, oB[dg], 0, 0, 0);
;             }
;         }
;         __syncthreads();
;     }
	s_and_b64 s[18:19], s[38:39], vcc
	v_add_f32_e32 v194, v97, v194
	v_cndmask_b32_e64 v96, v154, v194, s[18:19]
	s_and_b64 s[18:19], s[38:39], s[76:77]
	v_add_f32_e32 v195, v93, v195
	v_cndmask_b32_e64 v92, v154, v195, s[18:19]
	s_mov_b64 s[76:77], exec
	s_mov_b64 s[78:79], exec
	v_add3_u32 v198, v111, v125, v123
	ds_read_b64_tr_b16 v[166:167], v198 offset:11520
	ds_read_b64_tr_b16 v[164:165], v198 offset:9216
	ds_read_b64_tr_b16 v[168:169], v198 offset:9280
	ds_read_b64_tr_b16 v[170:171], v198 offset:11584
	ds_read_b64_tr_b16 v[172:173], v198 offset:9248
	ds_read_b64_tr_b16 v[174:175], v198 offset:11552
	ds_read_b64_tr_b16 v[176:177], v198 offset:9312
	ds_read_b64_tr_b16 v[178:179], v198 offset:11616
	v_add3_u32 v199, v111, v124, v123
	ds_read_b64_tr_b16 v[182:183], v199 offset:25344
	ds_read_b64_tr_b16 v[180:181], v199 offset:23040
	ds_read_b64_tr_b16 v[184:185], v199 offset:23104
	ds_read_b64_tr_b16 v[186:187], v199 offset:25408
	v_exp_f32_e32 v137, v137
	v_exp_f32_e32 v136, v136
	v_exp_f32_e32 v139, v102
	v_exp_f32_e32 v138, v98
	v_exp_f32_e32 v103, v103
	v_exp_f32_e32 v102, v99
	v_exp_f32_e32 v143, v104
	v_exp_f32_e32 v142, v100
	v_cndmask_b32_e32 v148, v154, v84, vcc
	v_cndmask_b32_e32 v149, v154, v83, vcc
	v_cndmask_b32_e32 v83, v154, v75, vcc
	v_cndmask_b32_e32 v84, v154, v74, vcc
	v_exp_f32_e32 v105, v105
	v_exp_f32_e32 v104, v101
	v_exp_f32_e32 v141, v140
	v_exp_f32_e32 v140, v94
	v_pk_add_f32 v[74:75], v[136:137], 0 op_sel_hi:[1,0]
	v_exp_f32_e32 v95, v91
	v_pk_add_f32 v[74:75], v[138:139], v[74:75]
	v_exp_f32_e32 v94, v90
	v_pk_add_f32 v[74:75], v[102:103], v[74:75]
	v_exp_f32_e32 v93, v96
	v_pk_add_f32 v[74:75], v[142:143], v[74:75]
	v_exp_f32_e32 v92, v92
	v_pk_add_f32 v[74:75], v[104:105], v[74:75]
	v_cvt_pk_bf16_f32 v101, v102, v142
	v_cvt_pk_bf16_f32 v102, v104, v140
	v_pk_add_f32 v[74:75], v[140:141], v[74:75]
	v_cvt_pk_bf16_f32 v96, v137, v139
	v_cvt_pk_bf16_f32 v98, v105, v141
	v_cvt_pk_bf16_f32 v100, v136, v138
	v_cndmask_b32_e32 v97, v154, v89, vcc
	v_cndmask_b32_e32 v76, v154, v76, vcc
	v_cndmask_b32_e32 v145, v154, v87, vcc
	v_exp_f32_e32 v87, v76
	v_exp_f32_e32 v76, v97
	v_cvt_pk_bf16_f32 v97, v103, v143
	v_cvt_pk_bf16_f32 v99, v95, v93
	v_cvt_pk_bf16_f32 v103, v94, v92
	ds_read_b64_tr_b16 v[188:189], v199 offset:23072
	ds_read_b64_tr_b16 v[190:191], v199 offset:25376
	s_waitcnt lgkmcnt(12)
	v_mfma_f32_16x16x32_bf16 v[70:73], v[164:167], v[96:99], v[70:73]
	v_cndmask_b32_e32 v144, v154, v88, vcc
	v_cndmask_b32_e32 v146, v154, v86, vcc
	v_cndmask_b32_e32 v81, v154, v81, vcc
	v_mfma_f32_16x16x32_bf16 v[54:57], v[164:167], v[100:103], v[54:57]
	v_cndmask_b32_e32 v80, v154, v80, vcc
	v_cndmask_b32_e32 v79, v154, v79, vcc
	ds_read_b64_tr_b16 v[164:165], v199 offset:23136
	ds_read_b64_tr_b16 v[166:167], v199 offset:25440
	s_waitcnt lgkmcnt(12)
	v_mfma_f32_16x16x32_bf16 v[62:65], v[168:171], v[96:99], v[62:65]
	v_cndmask_b32_e32 v78, v154, v78, vcc
	v_cndmask_b32_e32 v147, v154, v85, vcc
	v_cndmask_b32_e32 v82, v154, v82, vcc
	v_mfma_f32_16x16x32_bf16 v[6:9], v[168:171], v[100:103], v[6:9]
	v_cndmask_b32_e32 v77, v154, v77, vcc
	v_exp_f32_e32 v91, v84
	v_exp_f32_e32 v90, v78
	v_exp_f32_e32 v89, v83
	v_exp_f32_e32 v88, v79
	v_exp_f32_e32 v86, v80
	v_exp_f32_e32 v85, v77
	v_exp_f32_e32 v84, v81
	v_exp_f32_e32 v83, v82
	v_exp_f32_e32 v82, v146
	v_exp_f32_e32 v81, v149
	v_exp_f32_e32 v80, v145
	v_exp_f32_e32 v79, v148
	v_exp_f32_e32 v78, v144
	v_exp_f32_e32 v77, v147
	s_waitcnt lgkmcnt(10)
	v_mfma_f32_16x16x32_bf16 v[66:69], v[172:175], v[96:99], v[66:69]
	v_add_f32_e64 v74, v94, v74
	v_add_f32_e64 v75, v95, v75
	v_lshl_add_u64 v[114:115], v[114:115], 0, s[14:15]
	v_pk_add_f32 v[74:75], v[92:93], v[74:75]
	v_mfma_f32_16x16x32_bf16 v[2:5], v[172:175], v[100:103], v[2:5]
	v_add_f32_e64 v74, v90, v74
	v_add_f32_e64 v75, v91, v75
	v_lshl_add_u64 v[116:117], v[116:117], 0, s[34:35]
	v_pk_add_f32 v[74:75], v[88:89], v[74:75]
	s_waitcnt lgkmcnt(8)
	v_mfma_f32_16x16x32_bf16 v[58:61], v[176:179], v[96:99], v[58:61]
	v_cvt_pk_bf16_f32 v96, v91, v89
	v_cvt_pk_bf16_f32 v97, v87, v85
	v_cvt_pk_bf16_f32 v98, v83, v81
	v_mfma_f32_16x16x32_bf16 v[10:13], v[176:179], v[100:103], v[10:13]
	v_cvt_pk_bf16_f32 v99, v79, v77
	v_cvt_pk_bf16_f32 v100, v90, v88
	v_cvt_pk_bf16_f32 v101, v86, v84
	v_cvt_pk_bf16_f32 v102, v82, v80
	v_cvt_pk_bf16_f32 v103, v78, v76
	s_waitcnt lgkmcnt(6)
	v_mfma_f32_16x16x32_bf16 v[70:73], v[180:183], v[96:99], v[70:73]
	v_pk_add_f32 v[74:75], v[86:87], v[74:75]
	s_andn2_b64 vcc, exec, s[28:29]
	v_mfma_f32_16x16x32_bf16 v[54:57], v[180:183], v[100:103], v[54:57]
	v_pk_add_f32 v[74:75], v[84:85], v[74:75]
	s_waitcnt lgkmcnt(4)
	v_mfma_f32_16x16x32_bf16 v[62:65], v[184:187], v[96:99], v[62:65]
	v_add_f32_e64 v74, v82, v74
	v_add_f32_e64 v75, v83, v75
	v_pk_add_f32 v[74:75], v[80:81], v[74:75]
	v_mfma_f32_16x16x32_bf16 v[6:9], v[184:187], v[100:103], v[6:9]
	v_pk_add_f32 v[74:75], v[78:79], v[74:75]
	s_waitcnt lgkmcnt(2)
	v_mfma_f32_16x16x32_bf16 v[66:69], v[188:191], v[96:99], v[66:69]
	v_add_f32_e64 v74, v76, v74
	v_add_f32_e64 v75, v77, v75
	s_waitcnt lgkmcnt(0)
	s_barrier
	v_pk_add_f32 v[112:113], v[112:113], v[74:75]
	v_mfma_f32_16x16x32_bf16 v[2:5], v[188:191], v[100:103], v[2:5]
	v_mfma_f32_16x16x32_bf16 v[58:61], v[164:167], v[96:99], v[58:61]
	v_mfma_f32_16x16x32_bf16 v[10:13], v[164:167], v[100:103], v[10:13]
	s_cbranch_vccz .LBB0_819
	s_mov_b32 s78, s54
	s_branch .LBB0_848
